# EpiRes non-OUT path rewritten by hand: all 16 residual loads hoisted, scalar fma instead of packed ops, batched cross-lane reduction, counted vmcnt(15)
# speedup vs baseline: 1.0029x; 1.0029x over previous
; __global__ void __launch_bounds__(NWAVES * 64, 2) fwd_megakernel(Args a) {
;     ...
;         if (kind == K_NOP) continue;
;         if (kind == K_CONV) conv_phase(a, L, lds, gw, NGW, lane, wave);
;         else if (kind == K_SWIGLU) { pg8::StaticOrder S; S.init(M, g.N, G, bx); pg8::EpiSwiglu E{BIG, PS}; pg8::gemm_phase<pg8::EpiSwiglu, pg8::StaticOrder, true, true>(lds, g, S, E); }
;         else if (kind == K_RES) { pg8::StaticOrder S; S.init(M, g.N, G, bx); pg8::EpiRes E{step == 4 * SPL - 1 ? a.out : (float*)nullptr, XB, PS, alpha}; pg8::gemm_phase<pg8::EpiRes, pg8::StaticOrder, true, true>(lds, g, S, E); }
;         else if (kind == K_BF16) { pg8::StaticOrder S; S.init(M, g.N, G, bx); pg8::gemm_phase<pg8::EpiBf16, pg8::StaticOrder, true, true>(lds, g, S, eb); }
;         else if (kind == K_PREP) {
;             if (L == 0) prep64(BIG, 0, a.in[12], a.in[13], gw, NGW, lane);
;             else if (L == 1) prep_mla(QRAW, KB, BIG, a.in[22], a.in[23], gw, NGW, lane);
;             else if (L == 2) prep64(BIG, 2, a.in[26], a.in[27], gw, NGW, lane);
;             else prep64(BIG, 3, a.in[30], a.in[31], gw, NGW, lane);
;         }
;         else if (kind == K_ATTN) {
;             if (L == 1) { const float mb2 = att::logit_bound2<96>(a.in[22], a.in[23], lane); DecB d{QRAW, KB, (const bf16*)a.out, BIG}; attn_phase<96, DecB>(lds, G, vcu, 512, 512, d, mb2); }
;             else if (L == 2) { const float mb2 = att::logit_bound2<64>(a.in[26], a.in[27], lane); DecC d{BIG, LSE}; attn_phase<64, DecC>(lds, G, vcu, 1536, 2048, d, mb2); }
;             else { const float mb2 = att::logit_bound2<64>(L == 0 ? a.in[12] : a.in[30], L == 0 ? a.in[13] : a.in[31], lane);
;                    DecAD d{BIG, L == 0 ? a.in[14] : (const float*)nullptr, L == 0 ? 128 : 0, L == 0 ? (bf16*)nullptr : BIG + 48 * MiB, 1024, L == 0 ? 0 : 1}; attn_phase<64, DecAD>(lds, G, vcu, L == 0 ? 1024 : 512, L == 0 ? 1024 : 512, d, mb2); }
;         }
;         else if (kind == K_MERGE) merge_c(BIG, LSE, gw, NGW, lane);
;         if (nosync || step == 4 * SPL - 1) continue;
;         if (step == 0) grid.sync();
;         else xcd_barrier(xbar);
;     }
.Ltramp_1153:
	s_branch .LBB0_1153

; __device__ __forceinline__ unsigned cvt_pk_bf16(float lo, float hi) { unsigned r; asm volatile("v_cvt_pk_bf16_f32 %0, %1, %2" : "=v"(r) : "v"(lo), "v"(hi)); return r; }
;     __device__ __forceinline__ void operator()(const f32x4 (&acc)[2][2][4][2], const Unit& u, int wr, int wc, int fr, int fq) const {
;         const int row0 = u.pm * BM + wr * 64 + fr, col0 = u.pn * BM + wc * 32 + 8 * fq;
; #pragma unroll
;         for (int ai = 0; ai < 2; ++ai)
; #pragma unroll
;             for (int m = 0; m < 4; ++m) {
;                 const int row = row0 + ai * HALF + m * 16;
;                 bf16_t* xb = XB + (size_t)row * 1024 + col0; float ss = 0.f;
; #pragma unroll
;                 for (int bj = 0; bj < 2; ++bj) {
;                     const u32x4 xw = *(const u32x4*)(xb + bj * HALF);
;                     f32x4 x0, x1;
;                     x0[0] = __uint_as_float(xw.x << 16); x0[1] = __uint_as_float(xw.x & 0xffff0000u); x0[2] = __uint_as_float(xw.y << 16); x0[3] = __uint_as_float(xw.y & 0xffff0000u);
;                     x1[0] = __uint_as_float(xw.z << 16); x1[1] = __uint_as_float(xw.z & 0xffff0000u); x1[2] = __uint_as_float(xw.w << 16); x1[3] = __uint_as_float(xw.w & 0xffff0000u);
;                     x0 = x0 + acc[ai][bj][m][0] * alpha; x1 = x1 + acc[ai][bj][m][1] * alpha;
;                     if (OUT) { float* xr = OUT + (size_t)row * 1024 + col0 + bj * HALF; __builtin_nontemporal_store(x0, (f32x4*)xr); __builtin_nontemporal_store(x1, (f32x4*)(xr + 4)); }
;                     else {
;                         u32x4 w; w.x = cvt_pk_bf16(x0[0], x0[1]); w.y = cvt_pk_bf16(x0[2], x0[3]); w.z = cvt_pk_bf16(x1[0], x1[1]); w.w = cvt_pk_bf16(x1[2], x1[3]);
;                         *(u32x4*)(xb + bj * HALF) = w;
;                         ss += (x0[0] * x0[0] + x0[1] * x0[1]) + (x0[2] * x0[2] + x0[3] * x0[3]) + (x1[0] * x1[0] + x1[1] * x1[1]) + (x1[2] * x1[2] + x1[3] * x1[3]);
.LBB0_1052:
	s_and_b64 vcc, exec, s[80:81]
	s_cbranch_vccnz .Lres_old
	v_lshl_add_u32 v144, s56, 8, v148
	v_ashrrev_i32_e32 v145, 31, v144
	v_lshl_or_b32 v142, s28, 8, v150
	v_lshlrev_b64 v[128:129], 11, v[144:145]
	v_ashrrev_i32_e32 v143, 31, v142
	v_lshl_add_u64 v[128:129], s[24:25], 0, v[128:129]
	v_lshl_add_u64 v[146:147], v[142:143], 1, v[128:129]
	global_load_dwordx4 v[152:155], v[146:147], off
	global_load_dwordx4 v[156:159], v[146:147], off offset:256
	v_add_co_u32_e32 v196, vcc, 0x8000, v146
	s_nop 1
	v_addc_co_u32_e32 v197, vcc, 0, v147, vcc
	global_load_dwordx4 v[160:163], v[196:197], off
	global_load_dwordx4 v[164:167], v[196:197], off offset:256
	v_add_co_u32_e32 v196, vcc, 0x8000, v196
	s_nop 1
	v_addc_co_u32_e32 v197, vcc, 0, v197, vcc
	global_load_dwordx4 v[172:175], v[196:197], off
	global_load_dwordx4 v[176:179], v[196:197], off offset:256
	v_add_co_u32_e32 v196, vcc, 0x8000, v196
	s_nop 1
	v_addc_co_u32_e32 v197, vcc, 0, v197, vcc
	global_load_dwordx4 v[180:183], v[196:197], off
	global_load_dwordx4 v[184:187], v[196:197], off offset:256
	v_add_co_u32_e32 v196, vcc, 0x28000, v196
	s_nop 1
	v_addc_co_u32_e32 v197, vcc, 0, v197, vcc
	global_load_dwordx4 v[188:191], v[196:197], off
	global_load_dwordx4 v[192:195], v[196:197], off offset:256
	v_add_co_u32_e32 v196, vcc, 0x8000, v196
	s_nop 1
	v_addc_co_u32_e32 v197, vcc, 0, v197, vcc
	global_load_dwordx4 v[210:213], v[196:197], off
	global_load_dwordx4 v[218:221], v[196:197], off offset:256
	v_add_co_u32_e32 v196, vcc, 0x8000, v196
	s_nop 1
	v_addc_co_u32_e32 v197, vcc, 0, v197, vcc
	global_load_dwordx4 v[222:225], v[196:197], off
	global_load_dwordx4 v[226:229], v[196:197], off offset:256
	v_add_co_u32_e32 v196, vcc, 0x8000, v196
	s_nop 1
	v_addc_co_u32_e32 v197, vcc, 0, v197, vcc
	global_load_dwordx4 v[230:233], v[196:197], off
	global_load_dwordx4 v[234:237], v[196:197], off offset:256
	v_and_b32_e32 v131, 64, v204
	v_xor_b32_e32 v238, 16, v204
	v_add_u32_e32 v131, 64, v131
	v_xor_b32_e32 v239, 32, v204
	v_cmp_lt_i32_e32 vcc, v238, v131
	s_lshl_b32 s42, s28, 4
	s_lshl_b32 s43, s67, 2
	v_cndmask_b32_e32 v238, v204, v238, vcc
	v_cmp_lt_i32_e32 vcc, v239, v131
	s_add_i32 s42, s42, s43
	s_ashr_i32 s43, s42, 31
	v_cndmask_b32_e32 v239, v204, v239, vcc
	v_lshlrev_b32_e32 v238, 2, v238
	v_lshlrev_b32_e32 v239, 2, v239
	s_waitcnt vmcnt(15)
	v_lshlrev_b32_e32 v128, 16, v152
	v_lshlrev_b32_e32 v129, 16, v153
	v_lshlrev_b32_e32 v130, 16, v154
	v_lshlrev_b32_e32 v131, 16, v155
	v_and_b32_e32 v152, 0xffff0000, v152
	v_and_b32_e32 v153, 0xffff0000, v153
	v_and_b32_e32 v154, 0xffff0000, v154
	v_and_b32_e32 v155, 0xffff0000, v155
	v_fma_f32 v120, s74, v120, v128
	v_fma_f32 v122, s54, v122, v129
	v_fma_f32 v124, s74, v124, v130
	v_fma_f32 v126, s54, v126, v131
	v_fma_f32 v121, s75, v121, v152
	v_fma_f32 v123, s55, v123, v153
	v_fma_f32 v125, s75, v125, v154
	v_fma_f32 v127, s55, v127, v155
	v_cvt_pk_bf16_f32 v152, v120, v121
	v_cvt_pk_bf16_f32 v153, v122, v123
	v_cvt_pk_bf16_f32 v154, v124, v125
	v_cvt_pk_bf16_f32 v155, v126, v127
	global_store_dwordx4 v[146:147], v[152:155], off
	v_mul_f32_e32 v120, v120, v120
	v_mul_f32_e32 v121, v121, v121
	v_fmac_f32_e32 v120, v122, v122
	v_fmac_f32_e32 v121, v123, v123
	v_fmac_f32_e32 v120, v124, v124
	v_fmac_f32_e32 v121, v125, v125
	v_fmac_f32_e32 v120, v126, v126
	v_fmac_f32_e32 v121, v127, v127
	s_waitcnt vmcnt(15)
	v_lshlrev_b32_e32 v128, 16, v156
	v_lshlrev_b32_e32 v129, 16, v157
	v_lshlrev_b32_e32 v130, 16, v158
	v_lshlrev_b32_e32 v131, 16, v159
	v_and_b32_e32 v156, 0xffff0000, v156
	v_and_b32_e32 v157, 0xffff0000, v157
	v_and_b32_e32 v158, 0xffff0000, v158
	v_and_b32_e32 v159, 0xffff0000, v159
	v_fma_f32 v116, s74, v116, v128
	v_fma_f32 v118, s54, v118, v129
	v_fma_f32 v112, s74, v112, v130
	v_fma_f32 v114, s54, v114, v131
	v_fma_f32 v117, s75, v117, v156
	v_fma_f32 v119, s55, v119, v157
	v_fma_f32 v113, s75, v113, v158
	v_fma_f32 v115, s55, v115, v159
	v_cvt_pk_bf16_f32 v156, v116, v117
	v_cvt_pk_bf16_f32 v157, v118, v119
	v_cvt_pk_bf16_f32 v158, v112, v113
	v_cvt_pk_bf16_f32 v159, v114, v115
	global_store_dwordx4 v[146:147], v[156:159], off offset:256
	v_fmac_f32_e32 v120, v116, v116
	v_fmac_f32_e32 v121, v117, v117
	v_fmac_f32_e32 v120, v118, v118
	v_fmac_f32_e32 v121, v119, v119
	v_fmac_f32_e32 v120, v112, v112
	v_fmac_f32_e32 v121, v113, v113
	v_fmac_f32_e32 v120, v114, v114
	v_fmac_f32_e32 v121, v115, v115
	v_add_f32_e32 v120, v120, v121
	v_add_co_u32_e32 v196, vcc, 0x8000, v146
	s_nop 1
	v_addc_co_u32_e32 v197, vcc, 0, v147, vcc
	s_waitcnt vmcnt(15)
	v_lshlrev_b32_e32 v128, 16, v160
	v_lshlrev_b32_e32 v129, 16, v161
	v_lshlrev_b32_e32 v130, 16, v162
	v_lshlrev_b32_e32 v131, 16, v163
	v_and_b32_e32 v160, 0xffff0000, v160
	v_and_b32_e32 v161, 0xffff0000, v161
	v_and_b32_e32 v162, 0xffff0000, v162
	v_and_b32_e32 v163, 0xffff0000, v163
	v_fma_f32 v108, s74, v108, v128
	v_fma_f32 v110, s54, v110, v129
	v_fma_f32 v104, s74, v104, v130
	v_fma_f32 v106, s54, v106, v131
	v_fma_f32 v109, s75, v109, v160
	v_fma_f32 v111, s55, v111, v161
	v_fma_f32 v105, s75, v105, v162
	v_fma_f32 v107, s55, v107, v163
	v_cvt_pk_bf16_f32 v160, v108, v109
	v_cvt_pk_bf16_f32 v161, v110, v111
	v_cvt_pk_bf16_f32 v162, v104, v105
	v_cvt_pk_bf16_f32 v163, v106, v107
	global_store_dwordx4 v[196:197], v[160:163], off
	v_mul_f32_e32 v108, v108, v108
	v_mul_f32_e32 v109, v109, v109
	v_fmac_f32_e32 v108, v110, v110
	v_fmac_f32_e32 v109, v111, v111
	v_fmac_f32_e32 v108, v104, v104
	v_fmac_f32_e32 v109, v105, v105
	v_fmac_f32_e32 v108, v106, v106
	v_fmac_f32_e32 v109, v107, v107
	s_waitcnt vmcnt(15)
; __device__ __forceinline__ unsigned cvt_pk_bf16(float lo, float hi) { unsigned r; asm volatile("v_cvt_pk_bf16_f32 %0, %1, %2" : "=v"(r) : "v"(lo), "v"(hi)); return r; }
;     __device__ __forceinline__ void operator()(const f32x4 (&acc)[2][2][4][2], const Unit& u, int wr, int wc, int fr, int fq) const {
;     ...
;             for (int m = 0; m < 4; ++m) {
;                 const int row = row0 + ai * HALF + m * 16;
;                 bf16_t* xb = XB + (size_t)row * 1024 + col0; float ss = 0.f;
; #pragma unroll
;                 for (int bj = 0; bj < 2; ++bj) {
;                     const u32x4 xw = *(const u32x4*)(xb + bj * HALF);
;                     f32x4 x0, x1;
;                     x0[0] = __uint_as_float(xw.x << 16); x0[1] = __uint_as_float(xw.x & 0xffff0000u); x0[2] = __uint_as_float(xw.y << 16); x0[3] = __uint_as_float(xw.y & 0xffff0000u);
;                     x1[0] = __uint_as_float(xw.z << 16); x1[1] = __uint_as_float(xw.z & 0xffff0000u); x1[2] = __uint_as_float(xw.w << 16); x1[3] = __uint_as_float(xw.w & 0xffff0000u);
;                     x0 = x0 + acc[ai][bj][m][0] * alpha; x1 = x1 + acc[ai][bj][m][1] * alpha;
;                     if (OUT) { float* xr = OUT + (size_t)row * 1024 + col0 + bj * HALF; __builtin_nontemporal_store(x0, (f32x4*)xr); __builtin_nontemporal_store(x1, (f32x4*)(xr + 4)); }
;                     else {
;                         u32x4 w; w.x = cvt_pk_bf16(x0[0], x0[1]); w.y = cvt_pk_bf16(x0[2], x0[3]); w.z = cvt_pk_bf16(x1[0], x1[1]); w.w = cvt_pk_bf16(x1[2], x1[3]);
;                         *(u32x4*)(xb + bj * HALF) = w;
;                         ss += (x0[0] * x0[0] + x0[1] * x0[1]) + (x0[2] * x0[2] + x0[3] * x0[3]) + (x1[0] * x1[0] + x1[1] * x1[1]) + (x1[2] * x1[2] + x1[3] * x1[3]);
	v_lshlrev_b32_e32 v128, 16, v164
	v_lshlrev_b32_e32 v129, 16, v165
	v_lshlrev_b32_e32 v130, 16, v166
	v_lshlrev_b32_e32 v131, 16, v167
	v_and_b32_e32 v164, 0xffff0000, v164
	v_and_b32_e32 v165, 0xffff0000, v165
	v_and_b32_e32 v166, 0xffff0000, v166
	v_and_b32_e32 v167, 0xffff0000, v167
	v_fma_f32 v100, s74, v100, v128
	v_fma_f32 v102, s54, v102, v129
	v_fma_f32 v96, s74, v96, v130
	v_fma_f32 v98, s54, v98, v131
	v_fma_f32 v101, s75, v101, v164
	v_fma_f32 v103, s55, v103, v165
	v_fma_f32 v97, s75, v97, v166
	v_fma_f32 v99, s55, v99, v167
	v_cvt_pk_bf16_f32 v164, v100, v101
	v_cvt_pk_bf16_f32 v165, v102, v103
	v_cvt_pk_bf16_f32 v166, v96, v97
	v_cvt_pk_bf16_f32 v167, v98, v99
	global_store_dwordx4 v[196:197], v[164:167], off offset:256
	v_fmac_f32_e32 v108, v100, v100
	v_fmac_f32_e32 v109, v101, v101
	v_fmac_f32_e32 v108, v102, v102
	v_fmac_f32_e32 v109, v103, v103
	v_fmac_f32_e32 v108, v96, v96
	v_fmac_f32_e32 v109, v97, v97
	v_fmac_f32_e32 v108, v98, v98
	v_fmac_f32_e32 v109, v99, v99
	v_add_f32_e32 v108, v108, v109
	v_add_co_u32_e32 v196, vcc, 0x8000, v196
	s_nop 1
	v_addc_co_u32_e32 v197, vcc, 0, v197, vcc
	s_waitcnt vmcnt(15)
	v_lshlrev_b32_e32 v128, 16, v172
	v_lshlrev_b32_e32 v129, 16, v173
	v_lshlrev_b32_e32 v130, 16, v174
	v_lshlrev_b32_e32 v131, 16, v175
	v_and_b32_e32 v172, 0xffff0000, v172
	v_and_b32_e32 v173, 0xffff0000, v173
	v_and_b32_e32 v174, 0xffff0000, v174
	v_and_b32_e32 v175, 0xffff0000, v175
	v_fma_f32 v92, s74, v92, v128
	v_fma_f32 v94, s54, v94, v129
	v_fma_f32 v88, s74, v88, v130
	v_fma_f32 v90, s54, v90, v131
	v_fma_f32 v93, s75, v93, v172
	v_fma_f32 v95, s55, v95, v173
	v_fma_f32 v89, s75, v89, v174
	v_fma_f32 v91, s55, v91, v175
	v_cvt_pk_bf16_f32 v172, v92, v93
	v_cvt_pk_bf16_f32 v173, v94, v95
	v_cvt_pk_bf16_f32 v174, v88, v89
	v_cvt_pk_bf16_f32 v175, v90, v91
	global_store_dwordx4 v[196:197], v[172:175], off
	v_mul_f32_e32 v92, v92, v92
	v_mul_f32_e32 v93, v93, v93
	v_fmac_f32_e32 v92, v94, v94
	v_fmac_f32_e32 v93, v95, v95
	v_fmac_f32_e32 v92, v88, v88
	v_fmac_f32_e32 v93, v89, v89
	v_fmac_f32_e32 v92, v90, v90
	v_fmac_f32_e32 v93, v91, v91
	s_waitcnt vmcnt(15)
	v_lshlrev_b32_e32 v128, 16, v176
	v_lshlrev_b32_e32 v129, 16, v177
	v_lshlrev_b32_e32 v130, 16, v178
	v_lshlrev_b32_e32 v131, 16, v179
	v_and_b32_e32 v176, 0xffff0000, v176
	v_and_b32_e32 v177, 0xffff0000, v177
	v_and_b32_e32 v178, 0xffff0000, v178
	v_and_b32_e32 v179, 0xffff0000, v179
	v_fma_f32 v84, s74, v84, v128
	v_fma_f32 v86, s54, v86, v129
	v_fma_f32 v80, s74, v80, v130
	v_fma_f32 v82, s54, v82, v131
	v_fma_f32 v85, s75, v85, v176
	v_fma_f32 v87, s55, v87, v177
	v_fma_f32 v81, s75, v81, v178
	v_fma_f32 v83, s55, v83, v179
	v_cvt_pk_bf16_f32 v176, v84, v85
	v_cvt_pk_bf16_f32 v177, v86, v87
	v_cvt_pk_bf16_f32 v178, v80, v81
	v_cvt_pk_bf16_f32 v179, v82, v83
	global_store_dwordx4 v[196:197], v[176:179], off offset:256
	v_fmac_f32_e32 v92, v84, v84
	v_fmac_f32_e32 v93, v85, v85
	v_fmac_f32_e32 v92, v86, v86
	v_fmac_f32_e32 v93, v87, v87
	v_fmac_f32_e32 v92, v80, v80
	v_fmac_f32_e32 v93, v81, v81
	v_fmac_f32_e32 v92, v82, v82
	v_fmac_f32_e32 v93, v83, v83
	v_add_f32_e32 v92, v92, v93
	v_add_co_u32_e32 v196, vcc, 0x8000, v196
	s_nop 1
	v_addc_co_u32_e32 v197, vcc, 0, v197, vcc
	s_waitcnt vmcnt(15)
	v_lshlrev_b32_e32 v128, 16, v180
	v_lshlrev_b32_e32 v129, 16, v181
	v_lshlrev_b32_e32 v130, 16, v182
	v_lshlrev_b32_e32 v131, 16, v183
	v_and_b32_e32 v180, 0xffff0000, v180
	v_and_b32_e32 v181, 0xffff0000, v181
	v_and_b32_e32 v182, 0xffff0000, v182
	v_and_b32_e32 v183, 0xffff0000, v183
	v_fma_f32 v76, s74, v76, v128
	v_fma_f32 v78, s54, v78, v129
	v_fma_f32 v72, s74, v72, v130
	v_fma_f32 v74, s54, v74, v131
	v_fma_f32 v77, s75, v77, v180
	v_fma_f32 v79, s55, v79, v181
	v_fma_f32 v73, s75, v73, v182
	v_fma_f32 v75, s55, v75, v183
	v_cvt_pk_bf16_f32 v180, v76, v77
	v_cvt_pk_bf16_f32 v181, v78, v79
	v_cvt_pk_bf16_f32 v182, v72, v73
	v_cvt_pk_bf16_f32 v183, v74, v75
	global_store_dwordx4 v[196:197], v[180:183], off
	v_mul_f32_e32 v76, v76, v76
	v_mul_f32_e32 v77, v77, v77
	v_fmac_f32_e32 v76, v78, v78
	v_fmac_f32_e32 v77, v79, v79
	v_fmac_f32_e32 v76, v72, v72
	v_fmac_f32_e32 v77, v73, v73
	v_fmac_f32_e32 v76, v74, v74
	v_fmac_f32_e32 v77, v75, v75
	s_waitcnt vmcnt(15)
	v_lshlrev_b32_e32 v128, 16, v184
	v_lshlrev_b32_e32 v129, 16, v185
	v_lshlrev_b32_e32 v130, 16, v186
	v_lshlrev_b32_e32 v131, 16, v187
	v_and_b32_e32 v184, 0xffff0000, v184
	v_and_b32_e32 v185, 0xffff0000, v185
	v_and_b32_e32 v186, 0xffff0000, v186
	v_and_b32_e32 v187, 0xffff0000, v187
	v_fma_f32 v68, s74, v68, v128
	v_fma_f32 v70, s54, v70, v129
	v_fma_f32 v64, s74, v64, v130
	v_fma_f32 v66, s54, v66, v131
	v_fma_f32 v69, s75, v69, v184
	v_fma_f32 v71, s55, v71, v185
	v_fma_f32 v65, s75, v65, v186
	v_fma_f32 v67, s55, v67, v187
	v_cvt_pk_bf16_f32 v184, v68, v69
	v_cvt_pk_bf16_f32 v185, v70, v71
	v_cvt_pk_bf16_f32 v186, v64, v65
	v_cvt_pk_bf16_f32 v187, v66, v67
	global_store_dwordx4 v[196:197], v[184:187], off offset:256
	v_fmac_f32_e32 v76, v68, v68
	v_fmac_f32_e32 v77, v69, v69
	v_fmac_f32_e32 v76, v70, v70
	v_fmac_f32_e32 v77, v71, v71
	v_fmac_f32_e32 v76, v64, v64
	v_fmac_f32_e32 v77, v65, v65
	v_fmac_f32_e32 v76, v66, v66
	v_fmac_f32_e32 v77, v67, v67
	v_add_f32_e32 v76, v76, v77
	v_add_co_u32_e32 v196, vcc, 0x28000, v196
	s_nop 1
	v_addc_co_u32_e32 v197, vcc, 0, v197, vcc
	s_waitcnt vmcnt(15)
; __device__ __forceinline__ unsigned cvt_pk_bf16(float lo, float hi) { unsigned r; asm volatile("v_cvt_pk_bf16_f32 %0, %1, %2" : "=v"(r) : "v"(lo), "v"(hi)); return r; }
;     __device__ __forceinline__ void operator()(const f32x4 (&acc)[2][2][4][2], const Unit& u, int wr, int wc, int fr, int fq) const {
;     ...
;             for (int m = 0; m < 4; ++m) {
;                 const int row = row0 + ai * HALF + m * 16;
;                 bf16_t* xb = XB + (size_t)row * 1024 + col0; float ss = 0.f;
; #pragma unroll
;                 for (int bj = 0; bj < 2; ++bj) {
;                     const u32x4 xw = *(const u32x4*)(xb + bj * HALF);
;                     f32x4 x0, x1;
;                     x0[0] = __uint_as_float(xw.x << 16); x0[1] = __uint_as_float(xw.x & 0xffff0000u); x0[2] = __uint_as_float(xw.y << 16); x0[3] = __uint_as_float(xw.y & 0xffff0000u);
;                     x1[0] = __uint_as_float(xw.z << 16); x1[1] = __uint_as_float(xw.z & 0xffff0000u); x1[2] = __uint_as_float(xw.w << 16); x1[3] = __uint_as_float(xw.w & 0xffff0000u);
;                     x0 = x0 + acc[ai][bj][m][0] * alpha; x1 = x1 + acc[ai][bj][m][1] * alpha;
;                     if (OUT) { float* xr = OUT + (size_t)row * 1024 + col0 + bj * HALF; __builtin_nontemporal_store(x0, (f32x4*)xr); __builtin_nontemporal_store(x1, (f32x4*)(xr + 4)); }
;                     else {
;                         u32x4 w; w.x = cvt_pk_bf16(x0[0], x0[1]); w.y = cvt_pk_bf16(x0[2], x0[3]); w.z = cvt_pk_bf16(x1[0], x1[1]); w.w = cvt_pk_bf16(x1[2], x1[3]);
;                         *(u32x4*)(xb + bj * HALF) = w;
;                         ss += (x0[0] * x0[0] + x0[1] * x0[1]) + (x0[2] * x0[2] + x0[3] * x0[3]) + (x1[0] * x1[0] + x1[1] * x1[1]) + (x1[2] * x1[2] + x1[3] * x1[3]);
	v_lshlrev_b32_e32 v128, 16, v188
	v_lshlrev_b32_e32 v129, 16, v189
	v_lshlrev_b32_e32 v130, 16, v190
	v_lshlrev_b32_e32 v131, 16, v191
	v_and_b32_e32 v188, 0xffff0000, v188
	v_and_b32_e32 v189, 0xffff0000, v189
	v_and_b32_e32 v190, 0xffff0000, v190
	v_and_b32_e32 v191, 0xffff0000, v191
	v_fma_f32 v60, s74, v60, v128
	v_fma_f32 v62, s54, v62, v129
	v_fma_f32 v56, s74, v56, v130
	v_fma_f32 v58, s54, v58, v131
	v_fma_f32 v61, s75, v61, v188
	v_fma_f32 v63, s55, v63, v189
	v_fma_f32 v57, s75, v57, v190
	v_fma_f32 v59, s55, v59, v191
	v_cvt_pk_bf16_f32 v188, v60, v61
	v_cvt_pk_bf16_f32 v189, v62, v63
	v_cvt_pk_bf16_f32 v190, v56, v57
	v_cvt_pk_bf16_f32 v191, v58, v59
	global_store_dwordx4 v[196:197], v[188:191], off
	v_mul_f32_e32 v60, v60, v60
	v_mul_f32_e32 v61, v61, v61
	v_fmac_f32_e32 v60, v62, v62
	v_fmac_f32_e32 v61, v63, v63
	v_fmac_f32_e32 v60, v56, v56
	v_fmac_f32_e32 v61, v57, v57
	v_fmac_f32_e32 v60, v58, v58
	v_fmac_f32_e32 v61, v59, v59
	s_waitcnt vmcnt(15)
	v_lshlrev_b32_e32 v128, 16, v192
	v_lshlrev_b32_e32 v129, 16, v193
	v_lshlrev_b32_e32 v130, 16, v194
	v_lshlrev_b32_e32 v131, 16, v195
	v_and_b32_e32 v192, 0xffff0000, v192
	v_and_b32_e32 v193, 0xffff0000, v193
	v_and_b32_e32 v194, 0xffff0000, v194
	v_and_b32_e32 v195, 0xffff0000, v195
	v_fma_f32 v52, s74, v52, v128
	v_fma_f32 v54, s54, v54, v129
	v_fma_f32 v48, s74, v48, v130
	v_fma_f32 v50, s54, v50, v131
	v_fma_f32 v53, s75, v53, v192
	v_fma_f32 v55, s55, v55, v193
	v_fma_f32 v49, s75, v49, v194
	v_fma_f32 v51, s55, v51, v195
	v_cvt_pk_bf16_f32 v192, v52, v53
	v_cvt_pk_bf16_f32 v193, v54, v55
	v_cvt_pk_bf16_f32 v194, v48, v49
	v_cvt_pk_bf16_f32 v195, v50, v51
	global_store_dwordx4 v[196:197], v[192:195], off offset:256
	v_fmac_f32_e32 v60, v52, v52
	v_fmac_f32_e32 v61, v53, v53
	v_fmac_f32_e32 v60, v54, v54
	v_fmac_f32_e32 v61, v55, v55
	v_fmac_f32_e32 v60, v48, v48
	v_fmac_f32_e32 v61, v49, v49
	v_fmac_f32_e32 v60, v50, v50
	v_fmac_f32_e32 v61, v51, v51
	v_add_f32_e32 v60, v60, v61
	v_add_co_u32_e32 v196, vcc, 0x8000, v196
	s_nop 1
	v_addc_co_u32_e32 v197, vcc, 0, v197, vcc
	s_waitcnt vmcnt(15)
	v_lshlrev_b32_e32 v128, 16, v210
	v_lshlrev_b32_e32 v129, 16, v211
	v_lshlrev_b32_e32 v130, 16, v212
	v_lshlrev_b32_e32 v131, 16, v213
	v_and_b32_e32 v210, 0xffff0000, v210
	v_and_b32_e32 v211, 0xffff0000, v211
	v_and_b32_e32 v212, 0xffff0000, v212
	v_and_b32_e32 v213, 0xffff0000, v213
	v_fma_f32 v44, s74, v44, v128
	v_fma_f32 v46, s54, v46, v129
	v_fma_f32 v40, s74, v40, v130
	v_fma_f32 v42, s54, v42, v131
	v_fma_f32 v45, s75, v45, v210
	v_fma_f32 v47, s55, v47, v211
	v_fma_f32 v41, s75, v41, v212
	v_fma_f32 v43, s55, v43, v213
	v_cvt_pk_bf16_f32 v210, v44, v45
	v_cvt_pk_bf16_f32 v211, v46, v47
	v_cvt_pk_bf16_f32 v212, v40, v41
	v_cvt_pk_bf16_f32 v213, v42, v43
	global_store_dwordx4 v[196:197], v[210:213], off
	v_mul_f32_e32 v44, v44, v44
	v_mul_f32_e32 v45, v45, v45
	v_fmac_f32_e32 v44, v46, v46
	v_fmac_f32_e32 v45, v47, v47
	v_fmac_f32_e32 v44, v40, v40
	v_fmac_f32_e32 v45, v41, v41
	v_fmac_f32_e32 v44, v42, v42
	v_fmac_f32_e32 v45, v43, v43
	s_waitcnt vmcnt(15)
	v_lshlrev_b32_e32 v128, 16, v218
	v_lshlrev_b32_e32 v129, 16, v219
	v_lshlrev_b32_e32 v130, 16, v220
	v_lshlrev_b32_e32 v131, 16, v221
	v_and_b32_e32 v218, 0xffff0000, v218
	v_and_b32_e32 v219, 0xffff0000, v219
	v_and_b32_e32 v220, 0xffff0000, v220
	v_and_b32_e32 v221, 0xffff0000, v221
	v_fma_f32 v36, s74, v36, v128
	v_fma_f32 v38, s54, v38, v129
	v_fma_f32 v32, s74, v32, v130
	v_fma_f32 v34, s54, v34, v131
	v_fma_f32 v37, s75, v37, v218
	v_fma_f32 v39, s55, v39, v219
	v_fma_f32 v33, s75, v33, v220
	v_fma_f32 v35, s55, v35, v221
	v_cvt_pk_bf16_f32 v218, v36, v37
	v_cvt_pk_bf16_f32 v219, v38, v39
	v_cvt_pk_bf16_f32 v220, v32, v33
	v_cvt_pk_bf16_f32 v221, v34, v35
	global_store_dwordx4 v[196:197], v[218:221], off offset:256
	v_fmac_f32_e32 v44, v36, v36
	v_fmac_f32_e32 v45, v37, v37
	v_fmac_f32_e32 v44, v38, v38
	v_fmac_f32_e32 v45, v39, v39
	v_fmac_f32_e32 v44, v32, v32
	v_fmac_f32_e32 v45, v33, v33
	v_fmac_f32_e32 v44, v34, v34
	v_fmac_f32_e32 v45, v35, v35
	v_add_f32_e32 v44, v44, v45
	v_add_co_u32_e32 v196, vcc, 0x8000, v196
	s_nop 1
	v_addc_co_u32_e32 v197, vcc, 0, v197, vcc
	s_waitcnt vmcnt(15)
	v_lshlrev_b32_e32 v128, 16, v222
	v_lshlrev_b32_e32 v129, 16, v223
	v_lshlrev_b32_e32 v130, 16, v224
	v_lshlrev_b32_e32 v131, 16, v225
	v_and_b32_e32 v222, 0xffff0000, v222
	v_and_b32_e32 v223, 0xffff0000, v223
	v_and_b32_e32 v224, 0xffff0000, v224
	v_and_b32_e32 v225, 0xffff0000, v225
	v_fma_f32 v28, s74, v28, v128
	v_fma_f32 v30, s54, v30, v129
	v_fma_f32 v24, s74, v24, v130
	v_fma_f32 v26, s54, v26, v131
	v_fma_f32 v29, s75, v29, v222
	v_fma_f32 v31, s55, v31, v223
	v_fma_f32 v25, s75, v25, v224
	v_fma_f32 v27, s55, v27, v225
	v_cvt_pk_bf16_f32 v222, v28, v29
	v_cvt_pk_bf16_f32 v223, v30, v31
	v_cvt_pk_bf16_f32 v224, v24, v25
	v_cvt_pk_bf16_f32 v225, v26, v27
	global_store_dwordx4 v[196:197], v[222:225], off
	v_mul_f32_e32 v28, v28, v28
	v_mul_f32_e32 v29, v29, v29
	v_fmac_f32_e32 v28, v30, v30
	v_fmac_f32_e32 v29, v31, v31
	v_fmac_f32_e32 v28, v24, v24
	v_fmac_f32_e32 v29, v25, v25
	v_fmac_f32_e32 v28, v26, v26
	v_fmac_f32_e32 v29, v27, v27
	s_waitcnt vmcnt(15)
;     __device__ __forceinline__ void operator()(const f32x4 (&acc)[2][2][4][2], const Unit& u, int wr, int wc, int fr, int fq) const {
;     ...
;                         ss += (x0[0] * x0[0] + x0[1] * x0[1]) + (x0[2] * x0[2] + x0[3] * x0[3]) + (x1[0] * x1[0] + x1[1] * x1[1]) + (x1[2] * x1[2] + x1[3] * x1[3]);
;                     }
;                 }
;                 if (!OUT) { ss += __shfl_xor(ss, 16); ss += __shfl_xor(ss, 32); if (fq == 0) ps[(size_t)row * 16 + u.pn * 4 + wc] = ss; }
	v_lshlrev_b32_e32 v128, 16, v226
	v_lshlrev_b32_e32 v129, 16, v227
	v_lshlrev_b32_e32 v130, 16, v228
	v_lshlrev_b32_e32 v131, 16, v229
	v_and_b32_e32 v226, 0xffff0000, v226
	v_and_b32_e32 v227, 0xffff0000, v227
	v_and_b32_e32 v228, 0xffff0000, v228
	v_and_b32_e32 v229, 0xffff0000, v229
	v_fma_f32 v20, s74, v20, v128
	v_fma_f32 v22, s54, v22, v129
	v_fma_f32 v16, s74, v16, v130
	v_fma_f32 v18, s54, v18, v131
	v_fma_f32 v21, s75, v21, v226
	v_fma_f32 v23, s55, v23, v227
	v_fma_f32 v17, s75, v17, v228
	v_fma_f32 v19, s55, v19, v229
	v_cvt_pk_bf16_f32 v226, v20, v21
	v_cvt_pk_bf16_f32 v227, v22, v23
	v_cvt_pk_bf16_f32 v228, v16, v17
	v_cvt_pk_bf16_f32 v229, v18, v19
	global_store_dwordx4 v[196:197], v[226:229], off offset:256
	v_fmac_f32_e32 v28, v20, v20
	v_fmac_f32_e32 v29, v21, v21
	v_fmac_f32_e32 v28, v22, v22
	v_fmac_f32_e32 v29, v23, v23
	v_fmac_f32_e32 v28, v16, v16
	v_fmac_f32_e32 v29, v17, v17
	v_fmac_f32_e32 v28, v18, v18
	v_fmac_f32_e32 v29, v19, v19
	v_add_f32_e32 v28, v28, v29
	v_add_co_u32_e32 v196, vcc, 0x8000, v196
	s_nop 1
	v_addc_co_u32_e32 v197, vcc, 0, v197, vcc
	s_waitcnt vmcnt(15)
	v_lshlrev_b32_e32 v128, 16, v230
	v_lshlrev_b32_e32 v129, 16, v231
	v_lshlrev_b32_e32 v130, 16, v232
	v_lshlrev_b32_e32 v131, 16, v233
	v_and_b32_e32 v230, 0xffff0000, v230
	v_and_b32_e32 v231, 0xffff0000, v231
	v_and_b32_e32 v232, 0xffff0000, v232
	v_and_b32_e32 v233, 0xffff0000, v233
	v_fma_f32 v12, s74, v12, v128
	v_fma_f32 v14, s54, v14, v129
	v_fma_f32 v8, s74, v8, v130
	v_fma_f32 v10, s54, v10, v131
	v_fma_f32 v13, s75, v13, v230
	v_fma_f32 v15, s55, v15, v231
	v_fma_f32 v9, s75, v9, v232
	v_fma_f32 v11, s55, v11, v233
	v_cvt_pk_bf16_f32 v230, v12, v13
	v_cvt_pk_bf16_f32 v231, v14, v15
	v_cvt_pk_bf16_f32 v232, v8, v9
	v_cvt_pk_bf16_f32 v233, v10, v11
	global_store_dwordx4 v[196:197], v[230:233], off
	v_mul_f32_e32 v12, v12, v12
	v_mul_f32_e32 v13, v13, v13
	v_fmac_f32_e32 v12, v14, v14
	v_fmac_f32_e32 v13, v15, v15
	v_fmac_f32_e32 v12, v8, v8
	v_fmac_f32_e32 v13, v9, v9
	v_fmac_f32_e32 v12, v10, v10
	v_fmac_f32_e32 v13, v11, v11
	s_waitcnt vmcnt(15)
	v_lshlrev_b32_e32 v128, 16, v234
	v_lshlrev_b32_e32 v129, 16, v235
	v_lshlrev_b32_e32 v130, 16, v236
	v_lshlrev_b32_e32 v131, 16, v237
	v_and_b32_e32 v234, 0xffff0000, v234
	v_and_b32_e32 v235, 0xffff0000, v235
	v_and_b32_e32 v236, 0xffff0000, v236
	v_and_b32_e32 v237, 0xffff0000, v237
	v_fma_f32 v4, s74, v4, v128
	v_fma_f32 v6, s54, v6, v129
	v_fma_f32 v0, s74, v0, v130
	v_fma_f32 v2, s54, v2, v131
	v_fma_f32 v5, s75, v5, v234
	v_fma_f32 v7, s55, v7, v235
	v_fma_f32 v1, s75, v1, v236
	v_fma_f32 v3, s55, v3, v237
	v_cvt_pk_bf16_f32 v234, v4, v5
	v_cvt_pk_bf16_f32 v235, v6, v7
	v_cvt_pk_bf16_f32 v236, v0, v1
	v_cvt_pk_bf16_f32 v237, v2, v3
	global_store_dwordx4 v[196:197], v[234:237], off offset:256
	v_fmac_f32_e32 v12, v4, v4
	v_fmac_f32_e32 v13, v5, v5
	v_fmac_f32_e32 v12, v6, v6
	v_fmac_f32_e32 v13, v7, v7
	v_fmac_f32_e32 v12, v0, v0
	v_fmac_f32_e32 v13, v1, v1
	v_fmac_f32_e32 v12, v2, v2
	v_fmac_f32_e32 v13, v3, v3
	v_add_f32_e32 v12, v12, v13
	ds_bpermute_b32 v121, v238, v120
	ds_bpermute_b32 v109, v238, v108
	ds_bpermute_b32 v93, v238, v92
	ds_bpermute_b32 v77, v238, v76
	ds_bpermute_b32 v61, v238, v60
	ds_bpermute_b32 v45, v238, v44
	ds_bpermute_b32 v29, v238, v28
	ds_bpermute_b32 v13, v238, v12
	s_waitcnt lgkmcnt(7)
	v_add_f32_e32 v120, v120, v121
	s_waitcnt lgkmcnt(6)
	v_add_f32_e32 v108, v108, v109
	s_waitcnt lgkmcnt(5)
	v_add_f32_e32 v92, v92, v93
	s_waitcnt lgkmcnt(4)
	v_add_f32_e32 v76, v76, v77
	s_waitcnt lgkmcnt(3)
	v_add_f32_e32 v60, v60, v61
	s_waitcnt lgkmcnt(2)
	v_add_f32_e32 v44, v44, v45
	s_waitcnt lgkmcnt(1)
	v_add_f32_e32 v28, v28, v29
	s_waitcnt lgkmcnt(0)
	v_add_f32_e32 v12, v12, v13
	ds_bpermute_b32 v121, v239, v120
	ds_bpermute_b32 v109, v239, v108
	ds_bpermute_b32 v93, v239, v92
	ds_bpermute_b32 v77, v239, v76
	ds_bpermute_b32 v61, v239, v60
	ds_bpermute_b32 v45, v239, v44
	ds_bpermute_b32 v29, v239, v28
	ds_bpermute_b32 v13, v239, v12
	v_lshlrev_b64 v[128:129], 6, v[144:145]
	v_lshl_add_u64 v[128:129], s[96:97], 0, v[128:129]
	v_lshl_add_u64 v[128:129], v[128:129], 0, s[42:43]
	s_movk_i32 s42, 0x2000
	s_mov_b32 s43, 0
	v_lshl_add_u64 v[130:131], v[128:129], 0, s[42:43]
	s_waitcnt lgkmcnt(7)
	v_add_f32_e32 v120, v120, v121
	s_waitcnt lgkmcnt(6)
	v_add_f32_e32 v108, v108, v109
	s_waitcnt lgkmcnt(5)
	v_add_f32_e32 v92, v92, v93
	s_waitcnt lgkmcnt(4)
	v_add_f32_e32 v76, v76, v77
	s_waitcnt lgkmcnt(3)
	v_add_f32_e32 v60, v60, v61
	s_waitcnt lgkmcnt(2)
	v_add_f32_e32 v44, v44, v45
	s_waitcnt lgkmcnt(1)
	v_add_f32_e32 v28, v28, v29
	s_waitcnt lgkmcnt(0)
	v_add_f32_e32 v12, v12, v13
	s_and_saveexec_b64 s[58:59], s[38:39]
	global_store_dword v[128:129], v120, off
	global_store_dword v[128:129], v108, off offset:1024
	global_store_dword v[128:129], v92, off offset:2048
	global_store_dword v[128:129], v76, off offset:3072
	global_store_dword v[130:131], v60, off
	global_store_dword v[130:131], v44, off offset:1024
	global_store_dword v[130:131], v28, off offset:2048
	global_store_dword v[130:131], v12, off offset:3072
	s_or_b64 exec, exec, s[58:59]
	s_branch .LBB0_1143
